# c8 + 64B alignment of the GLA / RG / ff_elem / LN inner loop heads (code placement)
# baseline (speedup 1.0000x reference)
; template <int NR>
; __device__ __forceinline__ void ln_rows(const float* src, float* dstf, bf16_t* dstb, float* stat, size_t rstride, const float* gam, const float* bet, int lane) {
;     f32x4 v[NR][8]; float mean[NR], rstd[NR];
; #pragma unroll
;     for (int r = 0; r < NR; ++r)
; #pragma unroll
;         for (int j = 0; j < 8; ++j) v[r][j] = ((const f32x4*)(src + r * rstride * D))[lane + 64 * j];
; __global__ void __launch_bounds__(512, 2) mega_fwd(Args a_byval) {
;     ...
;                 for (int m = b * 8 + wave; m < TG / LNR; m += G * 8) ln_rows<LNR>(src + (size_t)m * D, X + (size_t)m * D, XN + (size_t)m * D, nullptr, TG / LNR, gam, bet, lane); }
.LBB0_22:
	s_add_i32 s30, s30, s44
	s_add_i32 s46, s46, s57
	s_add_u32 s58, s58, s54
	s_addc_u32 s59, s59, s55
	s_add_u32 s86, s86, s88
	s_addc_u32 s87, s87, s89
	s_cmpk_lt_i32 s30, 0x1000
	s_cbranch_scc0 .LBB0_159
	.p2align	6

; __device__ __forceinline__ void gla_finalize(const bf16_t* Z, const bf16_t* OF, const bf16_t* OK, const float* nw, bf16_t* OB, int G, int b, int tid) {
;     ...
;     for (int it0 = b; it0 < NIT; it0 += FB * G) {
;         u32x4 ra[FB], rb[FB], rg[FB];
; #pragma unroll
;         for (int k = 0; k < FB; ++k) { const int it = it0 + k * G; if (it < NIT) {
;             const int pair = it * 16 + pr, t = pair >> 2, hd = pair & 3; const size_t o = (size_t)t * DRNN + hd * 256 + l32 * 8;
;             ra[k] = *(const u32x4*)(OF + o); rb[k] = *(const u32x4*)(OK + o); rg[k] = *(const u32x4*)(Z + (size_t)t * LDZ + ZC_OG + hd * 256 + l32 * 8); } }
.LBB0_343:
	s_add_i32 s6, s17, s78
	s_add_i32 s6, s6, s78
	s_add_i32 s6, s6, s78
	v_add_u32_e32 v79, s0, v79
	s_cmpk_gt_i32 s6, 0xfff
	v_add_u32_e32 v80, s0, v80
	s_cbranch_scc1 .LBB0_356
	.p2align	6

; #define WG_BARRIER() __syncthreads()
; template <int DIR>
; __device__ __forceinline__ void gla_seq(LAS unsigned char* lds, const GlaCtx& c, int seq, int h, int sl, int tid) {
;     ...
;         GLA_STAGE(ph ^ 1, ph ^ 1);
;         { const int cn = DIR ? (NC - 4 - ci > 0 ? NC - 4 - ci : 0) : (ci + 3 < NC - 1 ? ci + 3 : NC - 1); GLA_ISSUE(cn, ph ^ 1); }
;         WG_BARRIER();
.LBB0_365:
	s_or_b64 exec, exec, s[8:9]
	s_max_i32 s26, s39, 0
	s_lshl_b64 s[8:9], s[26:27], 6
	s_add_u32 s8, s8, s42
	s_addc_u32 s9, s9, s43
	v_cvt_pk_bf16_f32 v32, v60, v61
	v_cvt_pk_bf16_f32 v33, v62, v63
	v_add_u32_e32 v34, v242, v176
	s_lshr_b64 s[16:17], s[8:9], 4
	s_waitcnt vmcnt(8)
	ds_write_b16 v174, v48 offset:45056
	ds_write_b16_d16_hi v174, v48 offset:45200
	ds_write_b16 v174, v49 offset:45344
	ds_write_b16_d16_hi v174, v49 offset:45488
	ds_write_b16 v174, v50 offset:45632
	ds_write_b16_d16_hi v174, v50 offset:45776
	ds_write_b16 v174, v51 offset:45920
	ds_write_b16_d16_hi v174, v51 offset:46064
	ds_write_b64 v34, v[32:33] offset:54272
	v_cvt_pk_bf16_f32 v32, v64, v65
	v_cvt_pk_bf16_f32 v33, v66, v67
	s_add_u32 s16, s16, s0
	ds_write_b64 v34, v[32:33] offset:58624
	v_cvt_pk_bf16_f32 v32, v68, v69
	v_cvt_pk_bf16_f32 v33, v70, v71
	s_addc_u32 s17, s17, 0
	ds_write_b64 v34, v[32:33] offset:62976
	v_cvt_pk_bf16_f32 v32, v72, v73
	v_cvt_pk_bf16_f32 v33, v74, v75
	v_add_u32_e32 v34, v242, v177
	s_lshl_b64 s[56:57], s[16:17], 7
	ds_write_b64 v34, v[32:33] offset:62976
	v_lshl_add_u64 v[32:33], s[8:9], 0, v[136:137]
	v_lshl_add_u64 v[40:41], s[56:57], 0, v[140:141]
	v_lshlrev_b64 v[32:33], 10, v[32:33]
	v_lshlrev_b64 v[40:41], 7, v[40:41]
	s_lshl_b64 s[56:57], s[16:17], 13
	v_lshl_add_u64 v[36:37], v[160:161], 0, v[32:33]
	v_lshl_add_u64 v[44:45], v[144:145], 0, v[40:41]
	v_lshl_add_u64 v[48:49], v[146:147], 0, s[56:57]
	global_load_dwordx4 v[32:35], v[36:37], off offset:16
	s_nop 0
	global_load_dwordx4 v[36:39], v[36:37], off
	s_nop 0
	global_load_dwordx4 v[40:43], v[44:45], off offset:16
	s_nop 0
	global_load_dwordx4 v[44:47], v[44:45], off
	v_mov_b64_e32 v[50:51], s[82:83]
	global_load_dwordx4 v[52:55], v[48:49], off
	v_lshl_add_u64 v[48:49], s[8:9], 0, v[132:133]
	v_mad_u64_u32 v[50:51], s[8:9], v48, s65, v[50:51]
	v_mad_i32_i24 v51, v49, s65, v51
	s_mov_b32 s55, s27
	v_lshl_add_u64 v[48:49], v[50:51], 0, s[54:55]
	s_mov_b32 s91, s27
	v_lshl_add_u64 v[48:49], v[48:49], 0, s[90:91]
	v_lshl_add_u64 v[48:49], v[48:49], 0, v[164:165]
	v_add_co_u32_e32 v48, vcc, s35, v48
	s_lshl_b64 s[8:9], s[16:17], 9
	s_nop 0
	v_addc_co_u32_e32 v49, vcc, 0, v49, vcc
	s_waitcnt vmcnt(12)
	v_lshl_add_u64 v[56:57], v[148:149], 0, s[8:9]
	global_load_dwordx4 v[48:51], v[48:49], off offset:2048
	s_mov_b32 s8, 0xfffc0000
	global_load_dwordx4 v[56:59], v[56:57], off
	s_add_i32 s92, s92, 2
	s_add_i32 s39, s39, -2
	s_mov_b32 s9, -1
	v_lshl_add_u64 v[162:163], v[162:163], 0, s[8:9]
	s_cmp_ge_u32 s92, s58
	s_waitcnt lgkmcnt(0)
	s_barrier
	s_cbranch_scc1 .LBB0_378
	.p2align	6

; #define WG_BARRIER() __syncthreads()
; template <int DIR>
; __device__ __forceinline__ void gla_seq(LAS unsigned char* lds, const GlaCtx& c, int seq, int h, int sl, int tid) {
;     ...
;         GLA_STAGE(ph ^ 1, ph ^ 1);
;         { const int cn = DIR ? (NC - 4 - ci > 0 ? NC - 4 - ci : 0) : (ci + 3 < NC - 1 ? ci + 3 : NC - 1); GLA_ISSUE(cn, ph ^ 1); }
;         WG_BARRIER();
.LBB0_383:
	s_or_b64 exec, exec, s[8:9]
	s_add_i32 s0, s90, 4
	s_min_i32 s8, s0, s12
	s_ashr_i32 s9, s8, 31
	s_lshl_b64 s[8:9], s[8:9], 6
	s_add_u32 s8, s8, s42
	s_addc_u32 s9, s9, s43
	v_cvt_pk_bf16_f32 v32, v60, v61
	v_cvt_pk_bf16_f32 v33, v62, v63
	v_add_u32_e32 v34, v243, v176
	s_lshr_b64 s[16:17], s[8:9], 4
	s_waitcnt vmcnt(8)
	ds_write_b16 v174, v48 offset:45056
	ds_write_b16_d16_hi v174, v48 offset:45200
	ds_write_b16 v174, v49 offset:45344
	ds_write_b16_d16_hi v174, v49 offset:45488
	ds_write_b16 v174, v50 offset:45632
	ds_write_b16_d16_hi v174, v50 offset:45776
	ds_write_b16 v174, v51 offset:45920
	ds_write_b16_d16_hi v174, v51 offset:46064
	ds_write_b64 v34, v[32:33] offset:54272
	v_cvt_pk_bf16_f32 v32, v64, v65
	v_cvt_pk_bf16_f32 v33, v66, v67
	s_or_b64 s[16:17], s[16:17], s[38:39]
	ds_write_b64 v34, v[32:33] offset:58624
	v_cvt_pk_bf16_f32 v32, v68, v69
	v_cvt_pk_bf16_f32 v33, v70, v71
	v_lshl_add_u64 v[48:49], s[8:9], 0, v[132:133]
	s_lshl_b64 s[8:9], s[16:17], 7
	ds_write_b64 v34, v[32:33] offset:62976
	v_cvt_pk_bf16_f32 v32, v72, v73
	v_cvt_pk_bf16_f32 v33, v74, v75
	v_add_u32_e32 v34, v243, v177
	v_lshl_add_u64 v[40:41], s[8:9], 0, v[140:141]
	ds_write_b64 v34, v[32:33] offset:62976
	v_lshlrev_b64 v[32:33], 10, v[48:49]
	v_lshlrev_b64 v[40:41], 7, v[40:41]
	s_lshl_b64 s[8:9], s[16:17], 13
	v_lshl_add_u64 v[36:37], v[158:159], 0, v[32:33]
	v_lshl_add_u64 v[44:45], v[144:145], 0, v[40:41]
	v_lshl_add_u64 v[50:51], v[146:147], 0, s[8:9]
	global_load_dwordx4 v[32:35], v[36:37], off offset:16
	s_nop 0
	global_load_dwordx4 v[36:39], v[36:37], off
	s_nop 0
	global_load_dwordx4 v[40:43], v[44:45], off offset:16
	s_nop 0
	global_load_dwordx4 v[44:47], v[44:45], off
	s_mov_b32 s55, s27
	global_load_dwordx4 v[52:55], v[50:51], off
	v_mov_b64_e32 v[50:51], s[82:83]
	v_mad_u64_u32 v[50:51], s[8:9], v48, s65, v[50:51]
	v_mad_i32_i24 v51, v49, s65, v51
	v_lshl_add_u64 v[48:49], v[50:51], 0, s[26:27]
	v_lshl_add_u64 v[48:49], v[48:49], 0, s[54:55]
	v_lshl_add_u64 v[48:49], v[48:49], 0, v[164:165]
	v_add_co_u32_e32 v48, vcc, s35, v48
	s_lshl_b64 s[8:9], s[16:17], 9
	s_nop 0
	v_addc_co_u32_e32 v49, vcc, 0, v49, vcc
	s_waitcnt vmcnt(12)
	v_lshl_add_u64 v[56:57], v[148:149], 0, s[8:9]
	global_load_dwordx4 v[48:51], v[48:49], off offset:2048
	s_add_i32 s90, s90, 2
	global_load_dwordx4 v[56:59], v[56:57], off
	v_lshl_add_u64 v[160:161], v[160:161], 0, s[40:41]
	s_cmp_ge_u32 s90, s58
	s_waitcnt lgkmcnt(0)
	s_barrier
	s_cbranch_scc1 .LBB0_360
	.p2align	6

; template <int MODE, int DIR>
; __device__ __forceinline__ void rg_wave(LAS unsigned char* lds, const RgCtx& c, int tile, int n, int ct, int lane) {
;     ...
;         for (int k0 = 0; k0 < cnt; k0 += 8) {
;             float a8[8], h8[8];
; #pragma unroll
;             for (int k = 0; k < 8; ++k) { const bool ok = (k0 + k) < cnt; const int pp = DIR ? first - (k0 + k) : first + (k0 + k);
;                 a8[k] = ok ? cA[(size_t)pp * DRNN + ch] : 1.f; h8[k] = ok ? cH[(size_t)pp * DRNN + ch] : 0.f; }
; #pragma unroll
;             for (int k = 0; k < 8; ++k) Hc = a8[k] * Hc + h8[k];
;         }
.LBB0_405:
	s_waitcnt vmcnt(0)
	v_fmac_f32_e32 v113, v156, v111
	v_fmac_f32_e32 v117, v113, v116
	v_fmac_f32_e32 v119, v117, v118
	v_fmac_f32_e32 v121, v119, v120
	v_fmac_f32_e32 v123, v121, v122
	v_fmac_f32_e32 v125, v123, v124
	s_movk_i32 s14, 0x8000
	v_fmac_f32_e32 v127, v125, v126
	v_mov_b32_e32 v156, v129
	s_add_i32 s16, s16, 8
	s_mov_b32 s15, -1
	v_fmac_f32_e32 v156, v127, v128
	s_cmp_ge_i32 s16, s0
	v_lshl_add_u64 v[114:115], v[114:115], 0, s[14:15]
	s_cbranch_scc1 .LBB0_435
	.p2align	6

; template <int MODE, int DIR>
; __device__ __forceinline__ void rg_wave(LAS unsigned char* lds, const RgCtx& c, int tile, int n, int ct, int lane) {
;     ...
;     const float ba = c.ba[DIR * DRNN + ch], bx = c.bx[DIR * DRNN + ch], lam = c.lam[DIR * DRNN + ch];
;     const float c8sp = -8.f * log1pf(__expf(-lam));
;     float* cA = c.carry + ((size_t)(0 * 2 + DIR) * 128) * DRNN; float* cH = c.carry + ((size_t)(1 * 2 + DIR) * 128) * DRNN;
;     float Hc = 0.f, Ac = 1.f;
.LBB0_435:
	s_waitcnt vmcnt(0)
	v_mul_f32_e32 v109, 0xbfb8aa3b, v109
	v_exp_f32_e32 v109, v109
	s_mov_b32 s0, 0x3f2aaaab
	v_and_b32_e32 v123, 64, v217
	s_mov_b32 s14, 0
	v_add_f32_e32 v111, 1.0, v109
	v_frexp_mant_f32_e32 v116, v111
	v_cvt_f64_f32_e32 v[114:115], v111
	v_add_f32_e32 v113, -1.0, v111
	v_frexp_exp_i32_f64_e32 v114, v[114:115]
	v_cmp_gt_f32_e32 vcc, s0, v116
	v_sub_f32_e32 v117, v113, v111
	v_sub_f32_e32 v113, v109, v113
	v_subbrev_co_u32_e32 v114, vcc, 0, v114, vcc
	v_add_f32_e32 v117, 1.0, v117
	v_sub_u32_e32 v115, 0, v114
	v_add_f32_e32 v113, v113, v117
	v_ldexp_f32 v111, v111, v115
	v_ldexp_f32 v113, v113, v115
	v_add_f32_e32 v115, -1.0, v111
	v_add_f32_e32 v118, 1.0, v111
	v_add_f32_e32 v116, 1.0, v115
	v_add_f32_e32 v119, -1.0, v118
	v_sub_f32_e32 v116, v111, v116
	v_sub_f32_e32 v111, v111, v119
	v_add_f32_e32 v111, v113, v111
	v_add_f32_e32 v116, v113, v116
	v_add_f32_e32 v113, v118, v111
	v_rcp_f32_e32 v119, v113
	v_add_f32_e32 v117, v115, v116
	v_sub_f32_e32 v115, v117, v115
	v_sub_f32_e32 v115, v116, v115
	v_sub_f32_e32 v116, v113, v118
	v_sub_f32_e32 v111, v111, v116
	v_mul_f32_e32 v116, v117, v119
	v_mul_f32_e32 v118, v113, v116
	v_fma_f32 v120, v116, v113, -v118
	v_fmac_f32_e32 v120, v116, v111
	v_add_f32_e32 v121, v118, v120
	v_sub_f32_e32 v122, v117, v121
	v_sub_f32_e32 v117, v117, v122
	v_sub_f32_e32 v118, v121, v118
	v_sub_f32_e32 v117, v117, v121
	v_add_f32_e32 v115, v115, v117
	v_sub_f32_e32 v117, v118, v120
	v_add_f32_e32 v115, v117, v115
	v_add_f32_e32 v117, v122, v115
	v_mul_f32_e32 v118, v119, v117
	v_mul_f32_e32 v120, v113, v118
	v_fma_f32 v113, v118, v113, -v120
	v_fmac_f32_e32 v113, v118, v111
	v_sub_f32_e32 v111, v122, v117
	v_add_f32_e32 v111, v115, v111
	v_add_f32_e32 v115, v120, v113
	v_sub_f32_e32 v121, v117, v115
	v_sub_f32_e32 v117, v117, v121
	v_sub_f32_e32 v120, v115, v120
	v_sub_f32_e32 v115, v117, v115
	v_add_f32_e32 v111, v111, v115
	v_sub_f32_e32 v113, v120, v113
	v_cvt_f32_i32_e32 v114, v114
	v_add_f32_e32 v111, v113, v111
	v_add_f32_e32 v113, v116, v118
	v_add_f32_e32 v111, v121, v111
	v_sub_f32_e32 v115, v113, v116
	v_mul_f32_e32 v111, v119, v111
	v_sub_f32_e32 v115, v118, v115
	v_add_f32_e32 v111, v115, v111
	v_mul_f32_e32 v118, 0x3f317218, v114
	s_mov_b32 s0, 0x3f317218
	v_add_f32_e32 v115, v113, v111
	v_fma_f32 v119, v114, s0, -v118
	v_mul_f32_e32 v116, v115, v115
	v_fmac_f32_e32 v119, 0xb102e308, v114
	v_sub_f32_e32 v113, v115, v113
	v_fmamk_f32 v117, v116, 0x3e9b6dac, v218
	v_sub_f32_e32 v111, v111, v113
	v_add_f32_e32 v113, v118, v119
	v_fmaak_f32 v117, v116, v117, 0x3f2aaada
	v_sub_f32_e32 v114, v113, v118
	v_ldexp_f32 v118, v115, 1
	v_mul_f32_e32 v115, v115, v116
	v_mul_f32_e32 v115, v115, v117
	v_add_f32_e32 v116, v118, v115
	v_sub_f32_e32 v117, v116, v118
	v_ldexp_f32 v111, v111, 1
	v_sub_f32_e32 v115, v115, v117
	v_add_f32_e32 v111, v111, v115
	v_add_f32_e32 v115, v116, v111
	v_sub_f32_e32 v116, v115, v116
	v_sub_f32_e32 v111, v111, v116
	v_add_f32_e32 v116, v113, v115
	v_sub_f32_e32 v117, v116, v113
	v_sub_f32_e32 v118, v116, v117
	v_sub_f32_e32 v114, v119, v114
	v_sub_f32_e32 v113, v113, v118
	v_sub_f32_e32 v115, v115, v117
	v_add_f32_e32 v113, v115, v113
	v_add_f32_e32 v115, v114, v111
	v_sub_f32_e32 v117, v115, v114
	v_sub_f32_e32 v118, v115, v117
	v_sub_f32_e32 v114, v114, v118
	v_sub_f32_e32 v111, v111, v117
	v_add_f32_e32 v113, v115, v113
	v_add_f32_e32 v111, v111, v114
	v_add_f32_e32 v114, v116, v113
	v_sub_f32_e32 v115, v114, v116
	v_sub_f32_e32 v113, v113, v115
	v_add_f32_e32 v111, v111, v113
	v_add_f32_e32 v111, v114, v111
	v_cmp_neq_f32_e32 vcc, s53, v109
	s_mov_b32 s0, 0x33800000
	v_mov_b32_e32 v122, 0xc0
	v_cndmask_b32_e32 v111, v254, v111, vcc
	v_cmp_ngt_f32_e32 vcc, -1.0, v109
	v_mov_b32_e32 v114, v110
	v_mov_b32_e32 v115, v110
	v_cndmask_b32_e32 v111, v215, v111, vcc
	v_cmp_neq_f32_e32 vcc, -1.0, v109
	v_mov_b32_e32 v113, v112
	v_mov_b32_e32 v116, v112
	v_cndmask_b32_e32 v111, v228, v111, vcc
	v_cmp_lt_f32_e64 vcc, |v109|, s0
	v_mov_b32_e32 v117, v112
	v_mov_b32_e32 v155, v147
	v_cndmask_b32_e32 v109, v111, v109, vcc
	v_mul_f32_e32 v109, 0xc1000000, v109
	v_mul_f32_e32 v118, 0x3fb8aa3b, v109
	v_or_b32_e32 v109, v123, v172
	v_lshl_or_b32 v109, v109, 2, v122
	v_or_b32_e32 v122, v123, v140
	v_lshlrev_b32_e32 v152, 2, v122
	v_mov_b32_e32 v111, v110
	v_mov_b32_e32 v119, v118
	v_mov_b32_e32 v120, v118
	v_mov_b32_e32 v121, v118
	v_or_b32_e32 v153, 0x80, v152
	v_or_b32_e32 v154, 64, v152
	.p2align	6

; template <int MODE, int DIR>
; __device__ __forceinline__ void rg_wave(LAS unsigned char* lds, const RgCtx& c, int tile, int n, int ct, int lane) {
;     ...
;         for (int k0 = 0; k0 < cnt; k0 += 8) {
;             float a8[8], h8[8];
; #pragma unroll
;             for (int k = 0; k < 8; ++k) { const bool ok = (k0 + k) < cnt; const int pp = DIR ? first - (k0 + k) : first + (k0 + k);
;                 a8[k] = ok ? cA[(size_t)pp * DRNN + ch] : 1.f; h8[k] = ok ? cH[(size_t)pp * DRNN + ch] : 0.f; }
; #pragma unroll
;             for (int k = 0; k < 8; ++k) Hc = a8[k] * Hc + h8[k];
;         }
.LBB0_441:
	s_waitcnt vmcnt(0)
	v_fmac_f32_e32 v109, v130, v107
	v_fmac_f32_e32 v115, v109, v114
	v_fmac_f32_e32 v117, v115, v116
	v_fmac_f32_e32 v119, v117, v118
	v_fmac_f32_e32 v121, v119, v120
	v_fmac_f32_e32 v123, v121, v122
	v_fmac_f32_e32 v125, v123, v124
	v_mov_b32_e32 v130, v127
	s_add_i32 s17, s17, 8
	s_cmp_ge_i32 s17, s0
	v_fmac_f32_e32 v130, v125, v126
	s_cbranch_scc1 .LBB0_471
	.p2align	6

; template <int MODE, int DIR>
; __device__ __forceinline__ void rg_wave(LAS unsigned char* lds, const RgCtx& c, int tile, int n, int ct, int lane) {
;     ...
;     const float ba = c.ba[DIR * DRNN + ch], bx = c.bx[DIR * DRNN + ch], lam = c.lam[DIR * DRNN + ch];
;     const float c8sp = -8.f * log1pf(__expf(-lam));
;     float* cA = c.carry + ((size_t)(0 * 2 + DIR) * 128) * DRNN; float* cH = c.carry + ((size_t)(1 * 2 + DIR) * 128) * DRNN;
;     float Hc = 0.f, Ac = 1.f;
.LBB0_471:
	s_waitcnt vmcnt(0)
	v_mul_f32_e32 v105, 0xbfb8aa3b, v105
	v_exp_f32_e32 v105, v105
	s_mov_b32 s0, 0x3f2aaaab
	s_mov_b32 s14, 0
	v_mov_b32_e32 v137, v148
	v_add_f32_e32 v107, 1.0, v105
	v_frexp_mant_f32_e32 v112, v107
	v_cvt_f64_f32_e32 v[110:111], v107
	v_add_f32_e32 v109, -1.0, v107
	v_frexp_exp_i32_f64_e32 v110, v[110:111]
	v_cmp_gt_f32_e32 vcc, s0, v112
	v_sub_f32_e32 v113, v109, v107
	v_sub_f32_e32 v109, v105, v109
	v_subbrev_co_u32_e32 v110, vcc, 0, v110, vcc
	v_add_f32_e32 v113, 1.0, v113
	v_sub_u32_e32 v111, 0, v110
	v_add_f32_e32 v109, v109, v113
	v_ldexp_f32 v107, v107, v111
	v_ldexp_f32 v109, v109, v111
	v_add_f32_e32 v111, -1.0, v107
	v_add_f32_e32 v114, 1.0, v107
	v_add_f32_e32 v112, 1.0, v111
	v_add_f32_e32 v115, -1.0, v114
	v_sub_f32_e32 v112, v107, v112
	v_sub_f32_e32 v107, v107, v115
	v_add_f32_e32 v107, v109, v107
	v_add_f32_e32 v112, v109, v112
	v_add_f32_e32 v109, v114, v107
	v_rcp_f32_e32 v115, v109
	v_add_f32_e32 v113, v111, v112
	v_sub_f32_e32 v111, v113, v111
	v_sub_f32_e32 v111, v112, v111
	v_sub_f32_e32 v112, v109, v114
	v_sub_f32_e32 v107, v107, v112
	v_mul_f32_e32 v112, v113, v115
	v_mul_f32_e32 v114, v109, v112
	v_fma_f32 v116, v112, v109, -v114
	v_fmac_f32_e32 v116, v112, v107
	v_add_f32_e32 v117, v114, v116
	v_sub_f32_e32 v118, v113, v117
	v_sub_f32_e32 v113, v113, v118
	v_sub_f32_e32 v114, v117, v114
	v_sub_f32_e32 v113, v113, v117
	v_add_f32_e32 v111, v111, v113
	v_sub_f32_e32 v113, v114, v116
	v_add_f32_e32 v111, v113, v111
	v_add_f32_e32 v113, v118, v111
	v_mul_f32_e32 v114, v115, v113
	v_mul_f32_e32 v116, v109, v114
	v_fma_f32 v109, v114, v109, -v116
	v_fmac_f32_e32 v109, v114, v107
	v_sub_f32_e32 v107, v118, v113
	v_add_f32_e32 v107, v111, v107
	v_add_f32_e32 v111, v116, v109
	v_sub_f32_e32 v117, v113, v111
	v_sub_f32_e32 v113, v113, v117
	v_sub_f32_e32 v116, v111, v116
	v_sub_f32_e32 v111, v113, v111
	v_add_f32_e32 v107, v107, v111
	v_sub_f32_e32 v109, v116, v109
	v_cvt_f32_i32_e32 v110, v110
	v_add_f32_e32 v107, v109, v107
	v_add_f32_e32 v109, v112, v114
	v_add_f32_e32 v107, v117, v107
	v_sub_f32_e32 v111, v109, v112
	v_mul_f32_e32 v107, v115, v107
	v_sub_f32_e32 v111, v114, v111
	v_add_f32_e32 v107, v111, v107
	v_mul_f32_e32 v114, 0x3f317218, v110
	s_mov_b32 s0, 0x3f317218
	v_add_f32_e32 v111, v109, v107
	v_fma_f32 v115, v110, s0, -v114
	v_mul_f32_e32 v112, v111, v111
	v_fmac_f32_e32 v115, 0xb102e308, v110
	v_sub_f32_e32 v109, v111, v109
	v_fmamk_f32 v113, v112, 0x3e9b6dac, v218
	v_sub_f32_e32 v107, v107, v109
	v_add_f32_e32 v109, v114, v115
	v_fmaak_f32 v113, v112, v113, 0x3f2aaada
	v_sub_f32_e32 v110, v109, v114
	v_ldexp_f32 v114, v111, 1
	v_mul_f32_e32 v111, v111, v112
	v_mul_f32_e32 v111, v111, v113
	v_add_f32_e32 v112, v114, v111
	v_sub_f32_e32 v113, v112, v114
	v_ldexp_f32 v107, v107, 1
	v_sub_f32_e32 v111, v111, v113
	v_add_f32_e32 v107, v107, v111
	v_add_f32_e32 v111, v112, v107
	v_sub_f32_e32 v112, v111, v112
	v_sub_f32_e32 v107, v107, v112
	v_add_f32_e32 v112, v109, v111
	v_sub_f32_e32 v113, v112, v109
	v_sub_f32_e32 v114, v112, v113
	v_sub_f32_e32 v110, v115, v110
	v_sub_f32_e32 v109, v109, v114
	v_sub_f32_e32 v111, v111, v113
	v_add_f32_e32 v109, v111, v109
	v_add_f32_e32 v111, v110, v107
	v_sub_f32_e32 v113, v111, v110
	v_sub_f32_e32 v114, v111, v113
	v_sub_f32_e32 v110, v110, v114
	v_sub_f32_e32 v107, v107, v113
	v_add_f32_e32 v109, v111, v109
	v_add_f32_e32 v107, v107, v110
	v_add_f32_e32 v110, v112, v109
	v_sub_f32_e32 v111, v110, v112
	v_sub_f32_e32 v109, v109, v111
	v_add_f32_e32 v107, v107, v109
	v_add_f32_e32 v107, v110, v107
	v_cmp_neq_f32_e32 vcc, s53, v105
	s_mov_b32 s0, 0x33800000
	v_mov_b32_e32 v110, v106
	v_cndmask_b32_e32 v107, v254, v107, vcc
	v_cmp_ngt_f32_e32 vcc, -1.0, v105
	v_mov_b32_e32 v111, v106
	v_mov_b32_e32 v109, v108
	v_cndmask_b32_e32 v107, v215, v107, vcc
	v_cmp_neq_f32_e32 vcc, -1.0, v105
	v_mov_b32_e32 v112, v108
	v_mov_b32_e32 v113, v108
	v_cndmask_b32_e32 v107, v228, v107, vcc
	v_cmp_lt_f32_e64 vcc, |v105|, s0
	s_nop 1
	v_cndmask_b32_e32 v105, v107, v105, vcc
	v_mul_f32_e32 v105, 0xc1000000, v105
	v_mul_f32_e32 v114, 0x3fb8aa3b, v105
	v_and_or_b32 v105, v217, 64, v140
	v_lshlrev_b32_e32 v105, 2, v105
	v_mov_b32_e32 v107, v106
	v_mov_b32_e32 v115, v114
	v_mov_b32_e32 v116, v114
	v_mov_b32_e32 v117, v114
	v_or_b32_e32 v134, 64, v105
	v_or_b32_e32 v135, 0x80, v105
	v_or_b32_e32 v136, 0xc0, v105
	.p2align	6

; #define LAS __attribute__((address_space(3)))
; template <int MODE>
; __device__ __forceinline__ void rg_phase(LAS unsigned char* lds, const RgCtx& c, int u0, int ustride, int tid) {
;     ...
; #pragma unroll
;             for (int h = 0; h < 2; ++h) {
;                 const int rr = tr + 64 * h, t = t0 + rr, pos = t & (c.SL - 1);
;                 float x[8] = {bb[0][0], bb[0][1], bb[0][2], bb[0][3], bb[1][0], bb[1][1], bb[1][2], bb[1][3]};
; #pragma unroll
;                 for (int j = 0; j < 4; ++j) {
;                     const int pp = pos + j - 2;
;                     float zf[8]; unpack8(zr[h][j], zf);
;                     const float msk = (pp >= 0 && pp < c.SL) ? 1.f : 0.f;
; #pragma unroll
;                     for (int e = 0; e < 8; ++e) x[e] += w[j][e >> 2][e & 3] * (zf[e] * msk);
;                 }
;                 *(LAS f32x4*)(lds + RG_XF + (rr * 64 + c8 * 8) * 4) = (f32x4){x[0], x[1], x[2], x[3]};
;                 *(LAS f32x4*)(lds + RG_XF + (rr * 64 + c8 * 8 + 4) * 4) = (f32x4){x[4], x[5], x[6], x[7]};
;                 *(LAS u32x4*)(lds + RG_XB + rr * 144 + c8 * 16) = pack8(x);
.LBB0_565:
	s_ashr_i32 s96, s38, 4
	s_lshl_b32 s1, s96, 7
	v_add_u32_e32 v76, s1, v92
	v_and_b32_e32 v76, s73, v76
	v_cmp_lt_i32_e32 vcc, 1, v76
	v_cmp_gt_i32_e64 s[8:9], s5, v76
	s_and_b64 s[8:9], vcc, s[8:9]
	v_cmp_lt_i32_e32 vcc, 0, v76
	v_cndmask_b32_e64 v80, 0, 1.0, s[8:9]
	v_cmp_ge_i32_e64 s[8:9], s72, v76
	s_and_b64 s[8:9], vcc, s[8:9]
	v_cmp_gt_i32_e32 vcc, s73, v76
	s_waitcnt vmcnt(2)
	v_lshlrev_b32_e32 v76, 16, v72
	v_and_b32_e32 v77, 0xffff0000, v72
	v_cndmask_b32_e64 v82, 0, 1.0, s[8:9]
	v_pk_mul_f32 v[76:77], v[80:81], v[76:77] op_sel_hi:[0,1]
	v_lshlrev_b32_e32 v78, 16, v68
	v_and_b32_e32 v79, 0xffff0000, v68
	v_lshlrev_b32_e32 v72, 16, v73
	v_and_b32_e32 v73, 0xffff0000, v73
	s_waitcnt vmcnt(0)
	v_pk_fma_f32 v[76:77], v[76:77], v[8:9], v[40:41]
	v_pk_mul_f32 v[78:79], v[82:83], v[78:79] op_sel_hi:[0,1]
	v_pk_mul_f32 v[72:73], v[80:81], v[72:73] op_sel_hi:[0,1]
	v_lshlrev_b32_e32 v68, 16, v69
	v_and_b32_e32 v69, 0xffff0000, v69
	v_pk_fma_f32 v[76:77], v[78:79], v[12:13], v[76:77]
	v_lshlrev_b32_e32 v78, 16, v60
	v_and_b32_e32 v79, 0xffff0000, v60
	v_pk_fma_f32 v[72:73], v[72:73], v[10:11], v[42:43]
	v_pk_mul_f32 v[68:69], v[82:83], v[68:69] op_sel_hi:[0,1]
	v_cndmask_b32_e64 v84, 0, 1.0, vcc
	v_pk_fma_f32 v[76:77], v[20:21], v[78:79], v[76:77]
	v_lshlrev_b32_e32 v78, 16, v64
	v_and_b32_e32 v79, 0xffff0000, v64
	v_pk_fma_f32 v[68:69], v[68:69], v[14:15], v[72:73]
	v_lshlrev_b32_e32 v60, 16, v61
	v_and_b32_e32 v61, 0xffff0000, v61
	v_lshlrev_b32_e32 v64, 16, v65
	v_and_b32_e32 v65, 0xffff0000, v65
	v_pk_mul_f32 v[78:79], v[84:85], v[78:79] op_sel_hi:[0,1]
	v_pk_fma_f32 v[60:61], v[22:23], v[60:61], v[68:69]
	v_pk_mul_f32 v[64:65], v[84:85], v[64:65] op_sel_hi:[0,1]
	v_pk_fma_f32 v[76:77], v[78:79], v[24:25], v[76:77]
	v_pk_fma_f32 v[78:79], v[64:65], v[26:27], v[60:61]
	v_lshlrev_b32_e32 v60, 16, v74
	v_and_b32_e32 v61, 0xffff0000, v74
	v_pk_mul_f32 v[60:61], v[80:81], v[60:61] op_sel_hi:[0,1]
	v_lshlrev_b32_e32 v64, 16, v70
	v_and_b32_e32 v65, 0xffff0000, v70
	v_pk_fma_f32 v[60:61], v[60:61], v[4:5], v[36:37]
	v_pk_mul_f32 v[64:65], v[82:83], v[64:65] op_sel_hi:[0,1]
	v_pk_fma_f32 v[60:61], v[64:65], v[16:17], v[60:61]
	v_lshlrev_b32_e32 v64, 16, v62
	v_and_b32_e32 v65, 0xffff0000, v62
	v_pk_fma_f32 v[60:61], v[28:29], v[64:65], v[60:61]
	v_lshlrev_b32_e32 v64, 16, v66
	v_and_b32_e32 v65, 0xffff0000, v66
	v_pk_mul_f32 v[64:65], v[84:85], v[64:65] op_sel_hi:[0,1]
	v_pk_fma_f32 v[60:61], v[64:65], v[32:33], v[60:61]
	v_lshlrev_b32_e32 v64, 16, v75
	v_and_b32_e32 v65, 0xffff0000, v75
	v_pk_mul_f32 v[64:65], v[80:81], v[64:65] op_sel_hi:[0,1]
	v_lshlrev_b32_e32 v68, 16, v71
	v_and_b32_e32 v69, 0xffff0000, v71
	v_pk_fma_f32 v[64:65], v[64:65], v[6:7], v[38:39]
	v_pk_mul_f32 v[68:69], v[82:83], v[68:69] op_sel_hi:[0,1]
	v_pk_fma_f32 v[64:65], v[68:69], v[18:19], v[64:65]
	v_lshlrev_b32_e32 v62, 16, v63
	v_and_b32_e32 v63, 0xffff0000, v63
	v_pk_fma_f32 v[62:63], v[30:31], v[62:63], v[64:65]
	v_lshlrev_b32_e32 v64, 16, v67
	v_and_b32_e32 v65, 0xffff0000, v67
	v_pk_mul_f32 v[64:65], v[84:85], v[64:65] op_sel_hi:[0,1]
	v_pk_fma_f32 v[62:63], v[64:65], v[34:35], v[62:63]
	ds_write_b128 v119, v[76:79]
	ds_write_b128 v119, v[60:63] offset:16
	v_cvt_pk_bf16_f32 v66, v60, v61
	v_add_u32_e32 v60, s1, v114
	v_and_b32_e32 v60, s73, v60
	v_cmp_lt_i32_e32 vcc, 1, v60
	v_cmp_gt_i32_e64 s[8:9], s5, v60
	v_cvt_pk_bf16_f32 v64, v76, v77
	v_cvt_pk_bf16_f32 v65, v78, v79
	v_cvt_pk_bf16_f32 v67, v62, v63
	s_and_b64 s[8:9], vcc, s[8:9]
	ds_write_b128 v120, v[64:67] offset:32768
	v_cndmask_b32_e64 v64, 0, 1.0, s[8:9]
	v_cmp_lt_i32_e32 vcc, 0, v60
	v_cmp_ge_i32_e64 s[8:9], s72, v60
	s_and_b64 s[8:9], vcc, s[8:9]
	v_cmp_gt_i32_e32 vcc, s73, v60
	v_lshlrev_b32_e32 v60, 16, v56
	v_and_b32_e32 v61, 0xffff0000, v56
	v_cndmask_b32_e64 v66, 0, 1.0, s[8:9]
	v_pk_mul_f32 v[60:61], v[64:65], v[60:61] op_sel_hi:[0,1]
	v_lshlrev_b32_e32 v62, 16, v52
	v_and_b32_e32 v63, 0xffff0000, v52
	v_lshlrev_b32_e32 v56, 16, v57
	v_and_b32_e32 v57, 0xffff0000, v57
	v_pk_fma_f32 v[60:61], v[60:61], v[8:9], v[40:41]
	v_pk_mul_f32 v[62:63], v[66:67], v[62:63] op_sel_hi:[0,1]
	v_pk_mul_f32 v[56:57], v[64:65], v[56:57] op_sel_hi:[0,1]
	v_lshlrev_b32_e32 v52, 16, v53
	v_and_b32_e32 v53, 0xffff0000, v53
	v_pk_fma_f32 v[60:61], v[62:63], v[12:13], v[60:61]
	v_lshlrev_b32_e32 v62, 16, v44
	v_and_b32_e32 v63, 0xffff0000, v44
	v_pk_fma_f32 v[56:57], v[56:57], v[10:11], v[42:43]
	v_pk_mul_f32 v[52:53], v[66:67], v[52:53] op_sel_hi:[0,1]
	v_cndmask_b32_e64 v68, 0, 1.0, vcc
	v_pk_fma_f32 v[60:61], v[20:21], v[62:63], v[60:61]
	v_lshlrev_b32_e32 v62, 16, v48
	v_and_b32_e32 v63, 0xffff0000, v48
	v_pk_fma_f32 v[52:53], v[52:53], v[14:15], v[56:57]
	v_lshlrev_b32_e32 v44, 16, v45
	v_and_b32_e32 v45, 0xffff0000, v45
	v_lshlrev_b32_e32 v48, 16, v49
	v_and_b32_e32 v49, 0xffff0000, v49
	v_pk_mul_f32 v[62:63], v[68:69], v[62:63] op_sel_hi:[0,1]
	v_pk_fma_f32 v[44:45], v[22:23], v[44:45], v[52:53]
	v_pk_mul_f32 v[48:49], v[68:69], v[48:49] op_sel_hi:[0,1]
	v_pk_fma_f32 v[60:61], v[62:63], v[24:25], v[60:61]
	v_pk_fma_f32 v[62:63], v[48:49], v[26:27], v[44:45]
	v_lshlrev_b32_e32 v44, 16, v58
	v_and_b32_e32 v45, 0xffff0000, v58
	v_pk_mul_f32 v[44:45], v[64:65], v[44:45] op_sel_hi:[0,1]
	v_lshlrev_b32_e32 v48, 16, v54
	v_and_b32_e32 v49, 0xffff0000, v54
	v_pk_fma_f32 v[44:45], v[44:45], v[4:5], v[36:37]
	v_pk_mul_f32 v[48:49], v[66:67], v[48:49] op_sel_hi:[0,1]
	v_pk_fma_f32 v[44:45], v[48:49], v[16:17], v[44:45]
	v_lshlrev_b32_e32 v48, 16, v46
	v_and_b32_e32 v49, 0xffff0000, v46
	v_pk_fma_f32 v[44:45], v[28:29], v[48:49], v[44:45]
	v_lshlrev_b32_e32 v48, 16, v50
	v_and_b32_e32 v49, 0xffff0000, v50
; #define LAS __attribute__((address_space(3)))
; #define WG_BARRIER() __syncthreads()
; #define RG_WLOAD(n_) do { const int ch0_ = (n_) * 64 + c8 * 8; \
;         _Pragma("unroll") for (int j = 0; j < 4; ++j) { w[j][0] = *(const f32x4*)(c.cw + j * DRNN + ch0_); w[j][1] = *(const f32x4*)(c.cw + j * DRNN + ch0_ + 4); } \
;         bb[0] = *(const f32x4*)(c.cb + ch0_); bb[1] = *(const f32x4*)(c.cb + ch0_ + 4); } while (0)
; template <int MODE>
; __device__ __forceinline__ void rg_phase(LAS unsigned char* lds, const RgCtx& c, int u0, int ustride, int tid) {
;     ...
;         const int tile = u >> 4, n = u & 15, t0 = tile * 128;
;         {
;             if (!nconst) RG_WLOAD(n);
; #pragma unroll
;             for (int h = 0; h < 2; ++h) {
;                 const int rr = tr + 64 * h, t = t0 + rr, pos = t & (c.SL - 1);
;                 float x[8] = {bb[0][0], bb[0][1], bb[0][2], bb[0][3], bb[1][0], bb[1][1], bb[1][2], bb[1][3]};
; #pragma unroll
;                 for (int j = 0; j < 4; ++j) {
;                     const int pp = pos + j - 2;
;                     float zf[8]; unpack8(zr[h][j], zf);
;                     const float msk = (pp >= 0 && pp < c.SL) ? 1.f : 0.f;
; #pragma unroll
;                     for (int e = 0; e < 8; ++e) x[e] += w[j][e >> 2][e & 3] * (zf[e] * msk);
;                 }
;                 *(LAS f32x4*)(lds + RG_XF + (rr * 64 + c8 * 8) * 4) = (f32x4){x[0], x[1], x[2], x[3]};
;                 *(LAS f32x4*)(lds + RG_XF + (rr * 64 + c8 * 8 + 4) * 4) = (f32x4){x[4], x[5], x[6], x[7]};
;                 *(LAS u32x4*)(lds + RG_XB + rr * 144 + c8 * 16) = pack8(x);
;             }
;         }
;         u32x4 gpre[2] = {{0u, 0u, 0u, 0u}, {0u, 0u, 0u, 0u}};
;         if (MODE == 1) { const int tok = tid >> 2, cs = (tid & 3) * 16;
; #pragma unroll
;             for (int h = 0; h < 2; ++h) gpre[h] = *(const u32x4*)(c.Z + (size_t)(t0 + tok) * LDZ + ZC_RG + n * 64 + cs + 8 * h); }
;         { const int un = (u + ustride < NU) ? u + ustride : u; RG_LOAD(un); }
;         WG_BARRIER();
	v_pk_mul_f32 v[48:49], v[68:69], v[48:49] op_sel_hi:[0,1]
	v_pk_fma_f32 v[44:45], v[48:49], v[32:33], v[44:45]
	v_lshlrev_b32_e32 v48, 16, v59
	v_and_b32_e32 v49, 0xffff0000, v59
	v_pk_mul_f32 v[48:49], v[64:65], v[48:49] op_sel_hi:[0,1]
	v_lshlrev_b32_e32 v52, 16, v55
	v_and_b32_e32 v53, 0xffff0000, v55
	v_pk_fma_f32 v[48:49], v[48:49], v[6:7], v[38:39]
	v_pk_mul_f32 v[52:53], v[66:67], v[52:53] op_sel_hi:[0,1]
	s_add_i32 s1, s38, s78
	v_pk_fma_f32 v[48:49], v[52:53], v[18:19], v[48:49]
	v_lshlrev_b32_e32 v46, 16, v47
	v_and_b32_e32 v47, 0xffff0000, v47
	s_cmpk_gt_i32 s1, 0x7ff
	v_pk_fma_f32 v[46:47], v[30:31], v[46:47], v[48:49]
	v_lshlrev_b32_e32 v48, 16, v51
	v_and_b32_e32 v49, 0xffff0000, v51
	s_cselect_b64 s[30:31], -1, 0
	s_cmpk_lt_i32 s1, 0x800
	v_pk_mul_f32 v[48:49], v[68:69], v[48:49] op_sel_hi:[0,1]
	s_cselect_b32 s8, s1, s38
	v_pk_fma_f32 v[46:47], v[48:49], v[34:35], v[46:47]
	s_lshl_b32 s9, s8, 6
	s_lshl_b32 s8, s8, 3
	v_cvt_pk_bf16_f32 v48, v60, v61
	v_cvt_pk_bf16_f32 v49, v62, v63
	v_cvt_pk_bf16_f32 v50, v44, v45
	v_cvt_pk_bf16_f32 v51, v46, v47
	s_and_b32 s38, s8, 0xffffff80
	ds_write_b128 v121, v[60:63]
	ds_write_b128 v121, v[44:47] offset:16
	ds_write_b128 v120, v[48:51] offset:41984
	v_add_u32_e32 v50, s38, v92
	s_and_b32 s9, s9, 0x3c0
	v_and_b32_e32 v46, s73, v50
	v_or_b32_e32 v44, s9, v93
	v_cmp_lt_i32_e32 vcc, 1, v46
	v_cmp_gt_i32_e64 s[8:9], s5, v46
	v_lshlrev_b32_e32 v164, 1, v44
	v_add_u32_e32 v44, -2, v50
	s_and_b64 vcc, vcc, s[8:9]
	v_lshl_add_u64 v[48:49], s[82:83], 0, v[164:165]
	v_cndmask_b32_e32 v44, v50, v44, vcc
	v_mad_i64_i32 v[44:45], s[8:9], v44, s65, v[48:49]
	v_cmp_lt_i32_e32 vcc, 0, v46
	v_cmp_ge_i32_e64 s[8:9], s72, v46
	s_and_b64 vcc, vcc, s[8:9]
	global_load_dwordx4 v[72:75], v[44:45], off
	v_subbrev_co_u32_e32 v44, vcc, 0, v50, vcc
	v_mad_i64_i32 v[44:45], s[8:9], v44, s65, v[48:49]
	global_load_dwordx4 v[68:71], v[44:45], off
	v_mad_i64_i32 v[44:45], s[8:9], v50, s65, v[48:49]
	global_load_dwordx4 v[60:63], v[44:45], off
	v_cmp_gt_i32_e32 vcc, s73, v46
	v_mov_b32_e32 v44, s38
	v_add_u32_e32 v51, 64, v50
	v_addc_co_u32_e32 v44, vcc, v44, v92, vcc
	v_mad_i64_i32 v[44:45], s[8:9], v44, s65, v[48:49]
	v_and_b32_e32 v76, s73, v51
	v_cmp_lt_i32_e32 vcc, 1, v76
	v_cmp_gt_i32_e64 s[8:9], s5, v76
	global_load_dwordx4 v[64:67], v[44:45], off
	v_add_u32_e32 v44, 62, v50
	s_and_b64 vcc, vcc, s[8:9]
	v_cndmask_b32_e32 v44, v51, v44, vcc
	v_mad_i64_i32 v[44:45], s[8:9], v44, s65, v[48:49]
	v_cmp_lt_i32_e32 vcc, 0, v76
	v_cmp_ge_i32_e64 s[8:9], s72, v76
	global_load_dwordx4 v[56:59], v[44:45], off
	v_add_u32_e32 v44, 63, v50
	s_and_b64 vcc, vcc, s[8:9]
	v_cndmask_b32_e32 v44, v51, v44, vcc
	v_cmp_gt_i32_e32 vcc, s73, v76
	v_add_u32_e32 v50, 0x41, v50
	v_mad_i64_i32 v[44:45], s[8:9], v44, s65, v[48:49]
	v_cndmask_b32_e32 v50, v51, v50, vcc
	global_load_dwordx4 v[52:55], v[44:45], off
	v_mad_i64_i32 v[44:45], s[8:9], v51, s65, v[48:49]
	v_mad_i64_i32 v[48:49], s[8:9], v50, s65, v[48:49]
	global_load_dwordx4 v[44:47], v[44:45], off
	s_lshl_b32 s26, s26, 13
	global_load_dwordx4 v[48:51], v[48:49], off
	v_lshl_add_u64 v[100:101], v[96:97], 0, s[26:27]
	s_mov_b64 s[8:9], -1
	s_and_b64 vcc, exec, s[88:89]
	v_or_b32_e32 v98, s0, v99
	v_lshlrev_b32_e32 v164, 1, v94
	s_waitcnt lgkmcnt(0)
	s_barrier
	s_cbranch_vccz .LBB0_571
; template <int MODE, int DIR>
; __device__ __forceinline__ void rg_wave(LAS unsigned char* lds, const RgCtx& c, int tile, int n, int ct, int lane) {
;     ...
;     bf16x8 Ba[2], Bx[2];
; #pragma unroll
;     for (int ks = 0; ks < 2; ++ks) {
;         Ba[ks] = *(const bf16x8*)(c.rgw + ((((size_t)0 * 2 + DIR) * 16 + n) * 64 + cl) * 64 + 32 * ks + 8 * fq);
;         Bx[ks] = *(const bf16x8*)(c.rgw + ((((size_t)1 * 2 + DIR) * 16 + n) * 64 + cl) * 64 + 32 * ks + 8 * fq);
;     }
;     const float ba = c.ba[DIR * DRNN + ch], bx = c.bx[DIR * DRNN + ch], lam = c.lam[DIR * DRNN + ch];
;     const float c8sp = -8.f * log1pf(__expf(-lam));
	v_lshl_add_u64 v[80:81], v[100:101], 0, v[164:165]
	s_mov_b64 s[8:9], 0x20000
	v_add_co_u32_e32 v76, vcc, 0x20000, v80
	v_lshl_add_u64 v[84:85], v[80:81], 0, s[8:9]
	s_mov_b64 s[8:9], 0x60000
	v_addc_co_u32_e32 v77, vcc, 0, v81, vcc
	v_lshl_add_u64 v[88:89], v[80:81], 0, s[8:9]
	v_add_co_u32_e32 v80, vcc, 0x60000, v80
	v_lshl_or_b32 v103, v98, 2, v214
	s_nop 0
	v_addc_co_u32_e32 v81, vcc, 0, v81, vcc
	global_load_dwordx4 v[76:79], v[76:77], off
	s_nop 0
	global_load_dwordx4 v[80:83], v[80:81], off
	s_nop 0
	global_load_dwordx4 v[84:87], v[84:85], off offset:64
	s_nop 0
	global_load_dwordx4 v[88:91], v[88:89], off offset:64
	s_nop 0
	global_load_dword v102, v103, s[14:15]
	global_load_dword v104, v103, s[16:17]
	s_nop 0
	global_load_dword v103, v103, s[20:21]
	s_mov_b32 s0, 0x3f2aaaab
	v_mov_b32_e32 v127, 1.0
	s_movk_i32 s8, 0x4000
	s_waitcnt vmcnt(0)
	v_mul_f32_e32 v103, 0xbfb8aa3b, v103
	v_exp_f32_e32 v103, v103
	s_nop 0
	v_add_f32_e32 v105, 1.0, v103
	v_add_f32_e32 v106, -1.0, v105
	v_sub_f32_e32 v107, v106, v105
	v_add_f32_e32 v107, 1.0, v107
	v_sub_f32_e32 v106, v103, v106
	v_add_f32_e32 v108, v106, v107
	v_frexp_mant_f32_e32 v106, v105
	v_cmp_gt_f32_e32 vcc, s0, v106
	v_cvt_f64_f32_e32 v[106:107], v105
	v_frexp_exp_i32_f64_e32 v106, v[106:107]
	v_subbrev_co_u32_e32 v122, vcc, 0, v106, vcc
	v_sub_u32_e32 v106, 0, v122
	v_ldexp_f32 v105, v105, v106
	v_ldexp_f32 v106, v108, v106
	v_add_f32_e32 v108, -1.0, v105
	v_add_f32_e32 v107, 1.0, v108
	v_sub_f32_e32 v107, v105, v107
	v_add_f32_e32 v109, v106, v107
	v_add_f32_e32 v107, 1.0, v105
	v_add_f32_e32 v110, -1.0, v107
	v_sub_f32_e32 v105, v105, v110
	v_add_f32_e32 v105, v106, v105
	v_add_f32_e32 v123, v107, v105
	v_rcp_f32_e32 v124, v123
	v_sub_f32_e32 v106, v123, v107
	v_add_f32_e32 v107, v108, v109
	v_sub_f32_e32 v105, v105, v106
	v_mul_f32_e32 v126, v107, v124
	v_sub_f32_e32 v106, v107, v108
	v_mul_f32_e32 v108, v123, v126
	v_fma_f32 v110, v126, v123, -v108
	v_fmac_f32_e32 v110, v126, v105
	v_sub_f32_e32 v125, v109, v106
	v_add_f32_e32 v106, v108, v110
	v_sub_f32_e32 v109, v107, v106
	v_pk_add_f32 v[112:113], v[106:107], v[108:109] neg_lo:[0,1] neg_hi:[0,1]
	v_mov_b32_e32 v111, v106
	v_pk_add_f32 v[106:107], v[112:113], v[110:111] neg_lo:[0,1] neg_hi:[0,1]
	s_mov_b32 s0, 0x3f317218
	v_add_f32_e32 v107, v125, v107
	v_add_f32_e32 v106, v106, v107
	v_add_f32_e32 v107, v109, v106
	v_mul_f32_e32 v125, v124, v107
	v_mul_f32_e32 v108, v123, v125
	v_fma_f32 v110, v125, v123, -v108
	v_fmac_f32_e32 v110, v125, v105
	v_sub_f32_e32 v105, v109, v107
	v_add_f32_e32 v105, v106, v105
	v_add_f32_e32 v106, v108, v110
	v_sub_f32_e32 v109, v107, v106
	v_pk_add_f32 v[112:113], v[106:107], v[108:109] neg_lo:[0,1] neg_hi:[0,1]
	v_mov_b32_e32 v111, v106
	v_pk_add_f32 v[106:107], v[112:113], v[110:111] neg_lo:[0,1] neg_hi:[0,1]
	v_cmp_neq_f32_e32 vcc, s53, v103
	v_add_f32_e32 v105, v105, v107
	v_add_f32_e32 v105, v106, v105
	v_add_f32_e32 v107, v126, v125
	v_add_f32_e32 v105, v109, v105
	v_sub_f32_e32 v106, v107, v126
	v_mul_f32_e32 v105, v124, v105
	v_sub_f32_e32 v106, v125, v106
	v_add_f32_e32 v105, v106, v105
	v_add_f32_e32 v108, v107, v105
	v_mul_f32_e32 v110, v108, v108
	v_fmamk_f32 v106, v110, 0x3e9b6dac, v218
	v_fmaak_f32 v171, v110, v106, 0x3f2aaada
	v_cvt_f32_i32_e32 v106, v122
	v_sub_f32_e32 v107, v108, v107
	v_sub_f32_e32 v105, v105, v107
	v_mul_f32_e32 v107, v108, v110
	v_pk_mul_f32 v[110:111], v[106:107], v[170:171]
	v_ldexp_f32 v109, v108, 1
	v_fma_f32 v108, v106, s0, -v110
	v_fmac_f32_e32 v108, 0xb102e308, v106
	v_pk_add_f32 v[106:107], v[110:111], v[108:109]
	v_ldexp_f32 v105, v105, 1
	v_sub_f32_e32 v109, v107, v109
	v_sub_f32_e32 v109, v111, v109
	v_add_f32_e32 v113, v105, v109
	v_mov_b32_e32 v112, v110
	v_pk_add_f32 v[110:111], v[106:107], v[110:111] neg_lo:[0,1] neg_hi:[0,1]
	v_pk_add_f32 v[122:123], v[106:107], v[112:113]
	v_mov_b32_e32 v109, v106
	v_mov_b32_e32 v111, v123
	v_pk_add_f32 v[124:125], v[108:109], v[110:111] neg_lo:[0,1] neg_hi:[0,1]
	v_pk_add_f32 v[108:109], v[108:109], v[110:111]
	v_mov_b32_e32 v112, v113
	v_pk_add_f32 v[110:111], v[108:109], v[106:107] op_sel:[1,0] op_sel_hi:[0,1] neg_lo:[0,1] neg_hi:[0,1]
	v_pk_add_f32 v[128:129], v[122:123], v[110:111] op_sel_hi:[1,0] neg_lo:[0,1] neg_hi:[0,1]
	v_mov_b32_e32 v122, v123
	v_mov_b32_e32 v123, v109
	v_pk_mov_b32 v[110:111], v[106:107], v[110:111] op_sel:[1,0]
	v_mov_b32_e32 v113, v106
	v_pk_add_f32 v[110:111], v[122:123], v[110:111] neg_lo:[0,1] neg_hi:[0,1]
	v_mov_b32_e32 v128, v124
	v_pk_add_f32 v[106:107], v[112:113], v[110:111] neg_lo:[0,1] neg_hi:[0,1]
	v_mov_b32_e32 v125, v109
	v_pk_add_f32 v[110:111], v[128:129], v[106:107]
	s_mov_b32 s0, 0x33800000
	v_pk_add_f32 v[112:113], v[110:111], v[110:111] op_sel:[0,1] op_sel_hi:[1,0]
	v_mov_b32_e32 v128, 0
	v_pk_add_f32 v[108:109], v[108:109], v[112:113] op_sel:[1,0] op_sel_hi:[0,1]
	v_mov_b32_e32 v111, v108
	v_pk_add_f32 v[122:123], v[110:111], v[124:125] neg_lo:[0,1] neg_hi:[0,1]
	v_mov_b32_e32 v107, v112
	v_sub_f32_e32 v105, v110, v122
	v_pk_add_f32 v[106:107], v[106:107], v[122:123] neg_lo:[0,1] neg_hi:[0,1]
	v_sub_f32_e32 v105, v124, v105
	v_add_f32_e32 v105, v106, v105
	v_add_f32_e32 v105, v105, v107
	v_add_f32_e32 v105, v108, v105
	v_cndmask_b32_e32 v105, v254, v105, vcc
	v_cmp_ngt_f32_e32 vcc, -1.0, v103
	v_and_or_b32 v122, v217, 64, v95
	v_lshlrev_b32_e32 v122, 2, v122
	v_cndmask_b32_e32 v105, v215, v105, vcc
	v_cmp_neq_f32_e32 vcc, -1.0, v103
	v_mov_b32_e32 v106, v102
	v_mov_b32_e32 v107, v102
	v_cndmask_b32_e32 v105, v228, v105, vcc
	v_cmp_lt_f32_e64 vcc, |v103|, s0
	v_mov_b32_e32 v108, v104
	v_mov_b32_e32 v109, v104
	v_cndmask_b32_e32 v103, v105, v103, vcc
	v_mul_f32_e32 v110, 0xc1000000, v103
	v_mul_f32_e32 v110, 0x3fb8aa3b, v110
	v_mov_b32_e32 v103, v102
	v_mov_b32_e32 v105, v104
	v_mov_b32_e32 v111, v110
	v_mov_b32_e32 v112, v110
	v_mov_b32_e32 v113, v110
	v_or_b32_e32 v123, 0xc0, v122
	v_or_b32_e32 v124, 0x80, v122
	v_or_b32_e32 v125, 64, v122
	v_mov_b32_e32 v126, v117
	.p2align	6

; template <int MODE, int DIR>
; __device__ __forceinline__ void rg_wave(LAS unsigned char* lds, const RgCtx& c, int tile, int n, int ct, int lane) {
;     ...
;     bf16x8 Ba[2], Bx[2];
; #pragma unroll
;     for (int ks = 0; ks < 2; ++ks) {
;         Ba[ks] = *(const bf16x8*)(c.rgw + ((((size_t)0 * 2 + DIR) * 16 + n) * 64 + cl) * 64 + 32 * ks + 8 * fq);
;         Bx[ks] = *(const bf16x8*)(c.rgw + ((((size_t)1 * 2 + DIR) * 16 + n) * 64 + cl) * 64 + 32 * ks + 8 * fq);
;     }
;     const float ba = c.ba[DIR * DRNN + ch], bx = c.bx[DIR * DRNN + ch], lam = c.lam[DIR * DRNN + ch];
;     const float c8sp = -8.f * log1pf(__expf(-lam));
.LBB0_571:
	s_and_b64 vcc, exec, s[8:9]
	s_cbranch_vccz .LBB0_562
	v_lshl_add_u64 v[84:85], v[100:101], 0, v[164:165]
	v_add_co_u32_e32 v80, vcc, 0x40000, v84
	v_lshl_add_u64 v[88:89], v[84:85], 0, s[40:41]
	s_nop 0
	v_addc_co_u32_e32 v81, vcc, 0, v85, vcc
	v_lshlrev_b32_e32 v101, 2, v98
	global_load_dwordx4 v[76:79], v[84:85], off
	s_nop 0
	global_load_dwordx4 v[80:83], v[80:81], off
	s_nop 0
	global_load_dwordx4 v[84:87], v[84:85], off offset:64
	s_nop 0
	global_load_dwordx4 v[88:91], v[88:89], off offset:64
	s_nop 0
	global_load_dword v100, v101, s[14:15]
	global_load_dword v102, v101, s[16:17]
	s_nop 0
	global_load_dword v101, v101, s[20:21]
	s_mov_b32 s0, 0x3f2aaaab
	s_mov_b32 s8, 0
	v_mov_b32_e32 v125, 1.0
	s_waitcnt vmcnt(0)
	v_mul_f32_e32 v101, 0xbfb8aa3b, v101
	v_exp_f32_e32 v101, v101
	s_nop 0
	v_add_f32_e32 v103, 1.0, v101
	v_add_f32_e32 v104, -1.0, v103
	v_sub_f32_e32 v105, v104, v103
	v_add_f32_e32 v105, 1.0, v105
	v_sub_f32_e32 v104, v101, v104
	v_add_f32_e32 v106, v104, v105
	v_frexp_mant_f32_e32 v104, v103
	v_cmp_gt_f32_e32 vcc, s0, v104
	v_cvt_f64_f32_e32 v[104:105], v103
	v_frexp_exp_i32_f64_e32 v104, v[104:105]
	v_subbrev_co_u32_e32 v112, vcc, 0, v104, vcc
	v_sub_u32_e32 v104, 0, v112
	v_ldexp_f32 v103, v103, v104
	v_ldexp_f32 v104, v106, v104
	v_add_f32_e32 v106, -1.0, v103
	v_add_f32_e32 v105, 1.0, v106
	v_sub_f32_e32 v105, v103, v105
	v_add_f32_e32 v107, v104, v105
	v_add_f32_e32 v105, 1.0, v103
	v_add_f32_e32 v108, -1.0, v105
	v_sub_f32_e32 v103, v103, v108
	v_add_f32_e32 v103, v104, v103
	v_add_f32_e32 v113, v105, v103
	v_rcp_f32_e32 v122, v113
	v_sub_f32_e32 v104, v113, v105
	v_add_f32_e32 v105, v106, v107
	v_sub_f32_e32 v103, v103, v104
	v_mul_f32_e32 v124, v105, v122
	v_sub_f32_e32 v104, v105, v106
	v_mul_f32_e32 v106, v113, v124
	v_fma_f32 v108, v124, v113, -v106
	v_fmac_f32_e32 v108, v124, v103
	v_sub_f32_e32 v123, v107, v104
	v_add_f32_e32 v104, v106, v108
	v_sub_f32_e32 v107, v105, v104
	v_pk_add_f32 v[110:111], v[104:105], v[106:107] neg_lo:[0,1] neg_hi:[0,1]
	v_mov_b32_e32 v109, v104
	v_pk_add_f32 v[104:105], v[110:111], v[108:109] neg_lo:[0,1] neg_hi:[0,1]
	s_mov_b32 s0, 0x3f317218
	v_add_f32_e32 v105, v123, v105
	v_add_f32_e32 v104, v104, v105
	v_add_f32_e32 v105, v107, v104
	v_mul_f32_e32 v123, v122, v105
	v_mul_f32_e32 v106, v113, v123
	v_fma_f32 v108, v123, v113, -v106
	v_fmac_f32_e32 v108, v123, v103
	v_sub_f32_e32 v103, v107, v105
	v_add_f32_e32 v103, v104, v103
	v_add_f32_e32 v104, v106, v108
	v_sub_f32_e32 v107, v105, v104
	v_pk_add_f32 v[110:111], v[104:105], v[106:107] neg_lo:[0,1] neg_hi:[0,1]
	v_mov_b32_e32 v109, v104
	v_pk_add_f32 v[104:105], v[110:111], v[108:109] neg_lo:[0,1] neg_hi:[0,1]
	v_cmp_neq_f32_e32 vcc, s53, v101
	v_add_f32_e32 v103, v103, v105
	v_add_f32_e32 v103, v104, v103
	v_add_f32_e32 v105, v124, v123
	v_add_f32_e32 v103, v107, v103
	v_sub_f32_e32 v104, v105, v124
	v_mul_f32_e32 v103, v122, v103
	v_sub_f32_e32 v104, v123, v104
	v_add_f32_e32 v103, v104, v103
	v_add_f32_e32 v106, v105, v103
	v_mul_f32_e32 v108, v106, v106
	v_fmamk_f32 v104, v108, 0x3e9b6dac, v218
	v_fmaak_f32 v171, v108, v104, 0x3f2aaada
	v_cvt_f32_i32_e32 v104, v112
	v_sub_f32_e32 v105, v106, v105
	v_sub_f32_e32 v103, v103, v105
	v_mul_f32_e32 v105, v106, v108
	v_pk_mul_f32 v[108:109], v[104:105], v[170:171]
	v_ldexp_f32 v107, v106, 1
	v_fma_f32 v106, v104, s0, -v108
	v_fmac_f32_e32 v106, 0xb102e308, v104
	v_pk_add_f32 v[104:105], v[108:109], v[106:107]
	v_ldexp_f32 v103, v103, 1
	v_sub_f32_e32 v107, v105, v107
	v_sub_f32_e32 v107, v109, v107
	v_add_f32_e32 v111, v103, v107
	v_mov_b32_e32 v110, v108
	v_pk_add_f32 v[108:109], v[104:105], v[108:109] neg_lo:[0,1] neg_hi:[0,1]
	v_pk_add_f32 v[112:113], v[104:105], v[110:111]
	v_mov_b32_e32 v107, v104
	v_mov_b32_e32 v109, v113
	v_pk_add_f32 v[122:123], v[106:107], v[108:109] neg_lo:[0,1] neg_hi:[0,1]
	v_pk_add_f32 v[106:107], v[106:107], v[108:109]
	v_mov_b32_e32 v110, v111
	v_pk_add_f32 v[108:109], v[106:107], v[104:105] op_sel:[1,0] op_sel_hi:[0,1] neg_lo:[0,1] neg_hi:[0,1]
	v_pk_add_f32 v[126:127], v[112:113], v[108:109] op_sel_hi:[1,0] neg_lo:[0,1] neg_hi:[0,1]
	v_mov_b32_e32 v112, v113
	v_mov_b32_e32 v113, v107
	v_pk_mov_b32 v[108:109], v[104:105], v[108:109] op_sel:[1,0]
	v_mov_b32_e32 v111, v104
	v_pk_add_f32 v[108:109], v[112:113], v[108:109] neg_lo:[0,1] neg_hi:[0,1]
	v_mov_b32_e32 v126, v122
	v_pk_add_f32 v[104:105], v[110:111], v[108:109] neg_lo:[0,1] neg_hi:[0,1]
	v_mov_b32_e32 v123, v107
	v_pk_add_f32 v[108:109], v[126:127], v[104:105]
	s_mov_b32 s0, 0x33800000
	v_pk_add_f32 v[110:111], v[108:109], v[108:109] op_sel:[0,1] op_sel_hi:[1,0]
	v_mov_b32_e32 v126, 0
	v_pk_add_f32 v[106:107], v[106:107], v[110:111] op_sel:[1,0] op_sel_hi:[0,1]
	v_mov_b32_e32 v109, v106
	v_pk_add_f32 v[112:113], v[108:109], v[122:123] neg_lo:[0,1] neg_hi:[0,1]
	v_mov_b32_e32 v105, v110
	v_sub_f32_e32 v103, v108, v112
	v_pk_add_f32 v[104:105], v[104:105], v[112:113] neg_lo:[0,1] neg_hi:[0,1]
	v_sub_f32_e32 v103, v122, v103
	v_add_f32_e32 v103, v104, v103
	v_add_f32_e32 v103, v103, v105
	v_add_f32_e32 v103, v106, v103
	v_cndmask_b32_e32 v103, v254, v103, vcc
	v_cmp_ngt_f32_e32 vcc, -1.0, v101
	v_and_or_b32 v112, v217, 64, v95
	v_lshlrev_b32_e32 v112, 2, v112
	v_cndmask_b32_e32 v103, v215, v103, vcc
	v_cmp_neq_f32_e32 vcc, -1.0, v101
	v_mov_b32_e32 v104, v100
	v_mov_b32_e32 v105, v100
	v_cndmask_b32_e32 v103, v228, v103, vcc
	v_cmp_lt_f32_e64 vcc, |v101|, s0
	v_mov_b32_e32 v106, v102
	v_mov_b32_e32 v107, v102
	v_cndmask_b32_e32 v101, v103, v101, vcc
	v_mul_f32_e32 v108, 0xc1000000, v101
	v_mul_f32_e32 v108, 0x3fb8aa3b, v108
	v_mov_b32_e32 v101, v100
	v_mov_b32_e32 v103, v102
	v_mov_b32_e32 v109, v108
	v_mov_b32_e32 v110, v108
	v_mov_b32_e32 v111, v108
	v_or_b32_e32 v113, 64, v112
	v_or_b32_e32 v122, 0x80, v112
	v_or_b32_e32 v123, 0xc0, v112
	v_mov_b32_e32 v124, v118
	.p2align	6

; __device__ __forceinline__ unsigned cvt_pk_bf16(float lo, float hi) { f32x2 v = {lo, hi}; bf16x2_t b = __builtin_convertvector(v, bf16x2_t); return __builtin_bit_cast(unsigned, b); }
; template <int NR>
; __device__ __forceinline__ void ln_rows(const float* src, float* dstf, bf16_t* dstb, float* stat, size_t rstride, const float* gam, const float* bet, int lane) {
;     ...
;     for (int j = 0; j < 8; ++j) {
;         const f32x4 gg = ((const f32x4*)gam)[lane + 64 * j], bb = ((const f32x4*)bet)[lane + 64 * j];
; #pragma unroll
;         for (int r = 0; r < NR; ++r) {
;             const f32x4 o = v[r][j] * rstd[r] * gg + bb;
;             if (dstf) __builtin_nontemporal_store(o, (f32x4*)(dstf + r * rstride * D) + lane + 64 * j);
;             if (dstb) { u32x2 p; p.x = cvt_pk_bf16(o.x, o.y); p.y = cvt_pk_bf16(o.z, o.w); ((u32x2*)(dstb + r * rstride * D))[lane + 64 * j] = p; }
;         }
; __global__ void __launch_bounds__(512, 2) mega_fwd(Args a_byval) {
;     ...
;                     for (int m = b * 8 + wave; m < TG / LNR; m += G * 8) ln_rows<LNR>(X + (size_t)m * D, nullptr, XN + (size_t)m * D, (float*)(ws + WS_STATS) + 2 * m, TG / LNR, gam, bet, lane);
.LBB0_703:
	s_add_i32 s12, s12, s10
	s_add_u32 s20, s20, s30
	s_addc_u32 s21, s21, s31
	s_add_u32 s38, s38, s30
	v_cvt_pk_bf16_f32 v4, v4, v5
	v_cvt_pk_bf16_f32 v5, v6, v7
	v_add_co_u32_e32 v6, vcc, 0x3000000, v158
	s_addc_u32 s39, s39, s31
	s_nop 0
	v_addc_co_u32_e32 v7, vcc, 0, v159, vcc
	s_cmpk_gt_i32 s12, 0xfff
	v_lshl_add_u64 v[158:159], v[158:159], 0, s[16:17]
	global_store_dwordx2 v[6:7], v[4:5], off offset:3584
	s_cbranch_scc1 .LBB0_768
	.p2align	6
